# sample-sequence conv group: the 26-row state copy moved from the serial row loop to the workgroup's seven idle waves
# speedup vs baseline: 1.0583x; 1.0007x over previous
.LBB0_521:
	s_andn2_b64 vcc, exec, s[50:51]
	v_lshl_add_u64 v[100:101], s[4:5], 0, v[112:113]
	s_cbranch_vccnz .LBB0_524
	global_load_dwordx4 v[32:35], v[100:101], off offset:16
	global_load_dwordx4 v[36:39], v[100:101], off
	s_cmp_lt_u32 s35, 4
	s_cbranch_scc1 .LBB0_524
	s_add_i32 s50, s35, -4
	s_add_u32 s50, s31, s50
	s_addc_u32 s51, s30, 0
	s_lshl_b64 s[50:51], s[50:51], 11
	v_lshl_add_u64 v[4:5], v[92:93], 0, s[50:51]
	s_waitcnt vmcnt(0)
	s_nop 0
	s_nop 0

.LBB0_526:
	s_andn2_b64 vcc, exec, s[48:49]
	s_cbranch_vccnz .LBB0_529
	global_load_dwordx4 v[60:63], v[100:101], off offset:2064
	global_load_dwordx4 v[56:59], v[100:101], off offset:2048
	s_cmp_lt_u32 s35, 4
	s_cbranch_scc1 .LBB0_529
	s_add_i32 s48, s35, -3
	s_add_u32 s48, s31, s48
	s_addc_u32 s49, s30, 0
	s_lshl_b64 s[48:49], s[48:49], 11
	v_lshl_add_u64 v[4:5], v[92:93], 0, s[48:49]
	s_waitcnt vmcnt(0)
	s_nop 0
	s_nop 0

.LBB0_531:
	s_andn2_b64 vcc, exec, s[48:49]
	s_cbranch_vccnz .LBB0_534
	v_add_co_u32_e32 v16, vcc, 0x1000, v100
	v_lshl_add_u64 v[4:5], v[100:101], 0, s[10:11]
	s_nop 0
	v_addc_co_u32_e32 v17, vcc, 0, v101, vcc
	global_load_dwordx4 v[72:75], v[16:17], off
	global_load_dwordx4 v[76:79], v[4:5], off offset:16
	s_cmp_eq_u32 s35, 0
	s_cbranch_scc1 .LBB0_534
	s_add_i32 s48, s35, -2
	s_add_u32 s48, s31, s48
	s_addc_u32 s49, s30, 0
	s_lshl_b64 s[48:49], s[48:49], 11
	v_lshl_add_u64 v[4:5], v[92:93], 0, s[48:49]
	s_waitcnt vmcnt(0)
	s_nop 0
	s_waitcnt vmcnt(0)
	s_nop 0

.LBB0_536:
	s_andn2_b64 vcc, exec, s[48:49]
	s_cbranch_vccnz .LBB0_539
	v_add_co_u32_e32 v80, vcc, 0x1000, v100
	v_lshl_add_u64 v[4:5], v[100:101], 0, s[16:17]
	s_nop 0
	v_addc_co_u32_e32 v81, vcc, 0, v101, vcc
	global_load_dwordx4 v[80:83], v[80:81], off offset:2048
	s_nop 0
	global_load_dwordx4 v[84:87], v[4:5], off offset:16
	s_cmp_eq_u32 s35, 0
	s_cbranch_scc1 .LBB0_539
	s_add_i32 s48, s35, -1
	s_add_u32 s48, s31, s48
	s_addc_u32 s49, s30, 0
	s_lshl_b64 s[48:49], s[48:49], 11
	v_lshl_add_u64 v[4:5], v[92:93], 0, s[48:49]
	s_waitcnt vmcnt(0)
	s_nop 0
	s_waitcnt vmcnt(0)
	s_nop 0

.LBB0_542:
	s_andn2_b64 vcc, exec, s[48:49]
	v_lshl_add_u64 v[78:79], s[46:47], 0, v[112:113]
	s_cbranch_vccnz .LBB0_544
	v_add_co_u32_e32 v2, vcc, 0x2000, v100
	v_lshl_add_u64 v[0:1], v[100:101], 0, s[40:41]
	s_nop 0
	v_addc_co_u32_e32 v3, vcc, 0, v101, vcc
	global_load_dwordx4 v[24:27], v[2:3], off
	s_nop 0
	global_load_dwordx4 v[0:3], v[0:1], off offset:16
	s_waitcnt vmcnt(0)
	s_nop 0
	s_waitcnt vmcnt(0)
	s_nop 0
	v_mov_b32_e32 v6, v1
	v_mov_b32_e32 v7, v3
	v_mov_b32_e32 v1, v2
	v_mov_b32_e32 v2, v25
	v_mov_b32_e32 v3, v27
	v_mov_b32_e32 v25, v26

.LBB0_546:
	s_andn2_b64 vcc, exec, s[48:49]
	s_cbranch_vccnz .LBB0_517
	v_add_co_u32_e32 v34, vcc, 0x2000, v100
	v_lshl_add_u64 v[38:39], v[100:101], 0, s[42:43]
	s_nop 0
	v_addc_co_u32_e32 v35, vcc, 0, v101, vcc
	global_load_dwordx4 v[34:37], v[34:35], off offset:2048
	s_nop 0
	global_load_dwordx4 v[38:41], v[38:39], off offset:16
	s_waitcnt vmcnt(0)
	s_nop 0
	s_waitcnt vmcnt(0)
	s_nop 0
	v_mov_b32_e32 v80, v39
	v_mov_b32_e32 v81, v41
	v_mov_b32_e32 v39, v40
	v_mov_b32_e32 v40, v35
	v_mov_b32_e32 v41, v37
	v_mov_b32_e32 v35, v36
	s_branch .LBB0_517
.LBB0_548:
	s_and_b32 s98, s92, 7
	s_cmp_eq_u32 s98, 0
	s_cbranch_scc0 .Lscopy_done
	s_cmp_eq_u32 s93, 0
	s_cbranch_scc1 .Lscopy_done
	s_load_dwordx2 s[80:81], s[96:97], 0x20
	s_load_dwordx2 s[100:101], s[96:97], 0xd8
	s_lshr_b32 s98, s92, 3
	s_mul_i32 s98, s98, 30
	s_lshl_b32 s99, s93, 2
	s_add_i32 s98, s98, s99
	s_lshl_b32 s98, s98, 11
	v_mbcnt_lo_u32_b32 v253, -1, 0
	v_mbcnt_hi_u32_b32 v253, -1, v253
	v_lshlrev_b32_e32 v253, 5, v253
	s_waitcnt lgkmcnt(0)
	s_add_u32 s80, s80, s98
	s_addc_u32 s81, s81, 0
	s_add_u32 s100, s100, s98
	s_addc_u32 s101, s101, 0
	s_add_u32 s100, s100, 0x8176000
	s_addc_u32 s101, s101, 0
	global_load_dwordx4 v[236:239], v253, s[80:81]
	global_load_dwordx4 v[240:243], v253, s[80:81] offset:16
	global_load_dwordx4 v[244:247], v253, s[80:81] offset:2048
	global_load_dwordx4 v[228:231], v253, s[80:81] offset:2064
	s_waitcnt vmcnt(0)
	global_store_dwordx4 v253, v[236:239], s[100:101]
	global_store_dwordx4 v253, v[240:243], s[100:101] offset:16
	global_store_dwordx4 v253, v[244:247], s[100:101] offset:2048
	global_store_dwordx4 v253, v[228:231], s[100:101] offset:2064
	s_cmp_eq_u32 s93, 7
	s_cbranch_scc1 .Lscopy_done
	s_add_u32 s80, s80, 0x1000
	s_addc_u32 s81, s81, 0
	s_add_u32 s100, s100, 0x1000
	s_addc_u32 s101, s101, 0
	s_nop 1
	global_load_dwordx4 v[236:239], v253, s[80:81]
	global_load_dwordx4 v[240:243], v253, s[80:81] offset:16
	global_load_dwordx4 v[244:247], v253, s[80:81] offset:2048
	global_load_dwordx4 v[228:231], v253, s[80:81] offset:2064
	s_waitcnt vmcnt(0)
	global_store_dwordx4 v253, v[236:239], s[100:101]
	global_store_dwordx4 v253, v[240:243], s[100:101] offset:16
	global_store_dwordx4 v253, v[244:247], s[100:101] offset:2048
	global_store_dwordx4 v253, v[228:231], s[100:101] offset:2064

	.amdhsa_kernel _Z6mk_fwdILi0ELi12EEv4Args
		.amdhsa_group_segment_fixed_size 0
		.amdhsa_private_segment_fixed_size 0
		.amdhsa_kernarg_size 504
		.amdhsa_user_sgpr_count 2
		.amdhsa_user_sgpr_dispatch_ptr 0
		.amdhsa_user_sgpr_queue_ptr 0
		.amdhsa_user_sgpr_kernarg_segment_ptr 1
		.amdhsa_user_sgpr_dispatch_id 0
		.amdhsa_user_sgpr_kernarg_preload_length 0
		.amdhsa_user_sgpr_kernarg_preload_offset 0
		.amdhsa_user_sgpr_private_segment_size 0
		.amdhsa_uses_dynamic_stack 0
		.amdhsa_enable_private_segment 0
		.amdhsa_system_sgpr_workgroup_id_x 1
		.amdhsa_system_sgpr_workgroup_id_y 0
		.amdhsa_system_sgpr_workgroup_id_z 0
		.amdhsa_system_sgpr_workgroup_info 0
		.amdhsa_system_vgpr_workitem_id 0
		.amdhsa_next_free_vgpr 254
		.amdhsa_next_free_sgpr 102
		.amdhsa_accum_offset 256
		.amdhsa_reserve_vcc 1
		.amdhsa_float_round_mode_32 0
		.amdhsa_float_round_mode_16_64 0
		.amdhsa_float_denorm_mode_32 3
		.amdhsa_float_denorm_mode_16_64 3
		.amdhsa_dx10_clamp 1
		.amdhsa_ieee_mode 1
		.amdhsa_fp16_overflow 0
		.amdhsa_tg_split 0
		.amdhsa_exception_fp_ieee_invalid_op 0
		.amdhsa_exception_fp_denorm_src 0
		.amdhsa_exception_fp_ieee_div_zero 0
		.amdhsa_exception_fp_ieee_overflow 0
		.amdhsa_exception_fp_ieee_underflow 0
		.amdhsa_exception_fp_ieee_inexact 0
		.amdhsa_exception_int_div_zero 0
	.end_amdhsa_kernel

amdhsa.kernels:
  - .agpr_count:     0
    .args:
      - .offset:         0
        .size:           248
        .value_kind:     by_value
      - .offset:         248
        .size:           4
        .value_kind:     hidden_block_count_x
      - .offset:         252
        .size:           4
        .value_kind:     hidden_block_count_y
      - .offset:         256
        .size:           4
        .value_kind:     hidden_block_count_z
      - .offset:         260
        .size:           2
        .value_kind:     hidden_group_size_x
      - .offset:         262
        .size:           2
        .value_kind:     hidden_group_size_y
      - .offset:         264
        .size:           2
        .value_kind:     hidden_group_size_z
      - .offset:         266
        .size:           2
        .value_kind:     hidden_remainder_x
      - .offset:         268
        .size:           2
        .value_kind:     hidden_remainder_y
      - .offset:         270
        .size:           2
        .value_kind:     hidden_remainder_z
      - .offset:         288
        .size:           8
        .value_kind:     hidden_global_offset_x
      - .offset:         296
        .size:           8
        .value_kind:     hidden_global_offset_y
      - .offset:         304
        .size:           8
        .value_kind:     hidden_global_offset_z
      - .offset:         312
        .size:           2
        .value_kind:     hidden_grid_dims
      - .offset:         368
        .size:           4
        .value_kind:     hidden_dynamic_lds_size
    .group_segment_fixed_size: 0
    .kernarg_segment_align: 8
    .kernarg_segment_size: 504
    .language:       OpenCL C
    .language_version:
      - 2
      - 0
    .max_flat_workgroup_size: 512
    .name:           _Z6mk_fwdILi0ELi12EEv4Args
    .private_segment_fixed_size: 0
    .sgpr_count:     108
    .sgpr_spill_count: 16
    .symbol:         _Z6mk_fwdILi0ELi12EEv4Args.kd
    .uniform_work_group_size: 1
    .uses_dynamic_stack: false
    .vgpr_count:     254
    .vgpr_spill_count: 0
    .wavefront_size: 64
